# z7 + x->fp8 convert loop unrolled 2x + retention step 2/3 LDS reads pipelined with the S barrier moved after step 2
# baseline (speedup 1.0000x reference)
.LBB0_55:
	global_load_dwordx4 v[16:19], v[6:7], off offset:-32
	global_load_dwordx4 v[20:23], v[6:7], off offset:-16
	global_load_dwordx4 v[24:27], v[6:7], off
	global_load_dwordx4 v[28:31], v[6:7], off offset:16
	v_lshl_add_u64 v[14:15], v[14:15], 0, s[16:17]
	v_cmp_lt_u64_e32 vcc, s[8:9], v[14:15]
	v_lshl_add_u64 v[6:7], v[6:7], 0, s[24:25]
	s_or_b64 s[22:23], vcc, s[22:23]
	s_mov_b64 s[100:101], exec
	s_andn2_b64 exec, exec, s[22:23]
	global_load_dwordx4 v[60:63], v[6:7], off offset:-32
	global_load_dwordx4 v[64:67], v[6:7], off offset:-16
	global_load_dwordx4 v[68:71], v[6:7], off
	global_load_dwordx4 v[72:75], v[6:7], off offset:16
	v_lshl_add_u64 v[14:15], v[14:15], 0, s[16:17]
	v_cmp_lt_u64_e32 vcc, s[8:9], v[14:15]
	v_lshl_add_u64 v[6:7], v[6:7], 0, s[24:25]
	s_or_b64 s[22:23], vcc, s[22:23]
	s_waitcnt vmcnt(0)
	v_mov_b32_e32 v88, 0
	v_mov_b32_e32 v89, 0
	v_mov_b32_e32 v90, 0
	v_mov_b32_e32 v91, 0
	v_pk_mul_f32 v[60:61], v[60:61], s[26:27] op_sel_hi:[1,0]
	v_pk_mul_f32 v[64:65], v[64:65], s[26:27] op_sel_hi:[1,0]
	v_pk_mul_f32 v[68:69], v[68:69], s[26:27] op_sel_hi:[1,0]
	v_pk_mul_f32 v[72:73], v[72:73], s[26:27] op_sel_hi:[1,0]
	v_med3_f32 v92, v60, s11, v1
	v_med3_f32 v93, v61, s11, v1
	v_med3_f32 v60, v64, s11, v1
	v_med3_f32 v61, v65, s11, v1
	v_med3_f32 v64, v68, s11, v1
	v_med3_f32 v65, v69, s11, v1
	v_med3_f32 v68, v72, s11, v1
	v_med3_f32 v69, v73, s11, v1
	v_cvt_pk_fp8_f32 v88, v92, v93
	v_cvt_pk_fp8_f32 v89, v60, v61
	v_cvt_pk_fp8_f32 v90, v64, v65
	v_cvt_pk_fp8_f32 v91, v68, v69
	v_pk_mul_f32 v[62:63], v[62:63], s[26:27] op_sel_hi:[1,0]
	v_pk_mul_f32 v[66:67], v[66:67], s[26:27] op_sel_hi:[1,0]
	v_pk_mul_f32 v[70:71], v[70:71], s[26:27] op_sel_hi:[1,0]
	v_pk_mul_f32 v[74:75], v[74:75], s[26:27] op_sel_hi:[1,0]
	v_med3_f32 v94, v62, s11, v1
	v_med3_f32 v95, v63, s11, v1
	v_med3_f32 v62, v66, s11, v1
	v_med3_f32 v63, v67, s11, v1
	v_med3_f32 v66, v70, s11, v1
	v_med3_f32 v67, v71, s11, v1
	v_med3_f32 v70, v74, s11, v1
	v_med3_f32 v71, v75, s11, v1
	v_cvt_pk_fp8_f32 v88, v94, v95 op_sel:[0,0,1]
	v_cvt_pk_fp8_f32 v89, v62, v63 op_sel:[0,0,1]
	v_cvt_pk_fp8_f32 v90, v66, v67 op_sel:[0,0,1]
	v_cvt_pk_fp8_f32 v91, v70, v71 op_sel:[0,0,1]
	v_lshl_add_u64 v[76:77], v[12:13], 0, s[20:21]
	global_store_dwordx4 v[76:77], v[88:91], off
	s_mov_b64 exec, s[100:101]
	v_mov_b32_e32 v32, 0
	v_mov_b32_e32 v33, 0
	v_mov_b32_e32 v34, 0
	v_mov_b32_e32 v35, 0
	v_pk_mul_f32 v[16:17], v[16:17], s[26:27] op_sel_hi:[1,0]
	v_pk_mul_f32 v[20:21], v[20:21], s[26:27] op_sel_hi:[1,0]
	v_pk_mul_f32 v[24:25], v[24:25], s[26:27] op_sel_hi:[1,0]
	v_pk_mul_f32 v[28:29], v[28:29], s[26:27] op_sel_hi:[1,0]
	v_med3_f32 v0, v16, s11, v1
	v_med3_f32 v3, v17, s11, v1
	v_med3_f32 v16, v20, s11, v1
	v_med3_f32 v17, v21, s11, v1
	v_med3_f32 v20, v24, s11, v1
	v_med3_f32 v21, v25, s11, v1
	v_med3_f32 v24, v28, s11, v1
	v_med3_f32 v25, v29, s11, v1
	v_cvt_pk_fp8_f32 v32, v0, v3
	v_cvt_pk_fp8_f32 v33, v16, v17
	v_cvt_pk_fp8_f32 v34, v20, v21
	v_cvt_pk_fp8_f32 v35, v24, v25
	v_pk_mul_f32 v[18:19], v[18:19], s[26:27] op_sel_hi:[1,0]
	v_pk_mul_f32 v[22:23], v[22:23], s[26:27] op_sel_hi:[1,0]
	v_pk_mul_f32 v[26:27], v[26:27], s[26:27] op_sel_hi:[1,0]
	v_pk_mul_f32 v[30:31], v[30:31], s[26:27] op_sel_hi:[1,0]
	v_med3_f32 v5, v18, s11, v1
	v_med3_f32 v9, v19, s11, v1
	v_med3_f32 v18, v22, s11, v1
	v_med3_f32 v19, v23, s11, v1
	v_med3_f32 v22, v26, s11, v1
	v_med3_f32 v23, v27, s11, v1
	v_med3_f32 v26, v30, s11, v1
	v_med3_f32 v27, v31, s11, v1
	v_cvt_pk_fp8_f32 v32, v5, v9 op_sel:[0,0,1]
	v_cvt_pk_fp8_f32 v33, v18, v19 op_sel:[0,0,1]
	v_cvt_pk_fp8_f32 v34, v22, v23 op_sel:[0,0,1]
	v_cvt_pk_fp8_f32 v35, v26, v27 op_sel:[0,0,1]
	global_store_dwordx4 v[12:13], v[32:35], off
	v_lshl_add_u64 v[12:13], v[12:13], 0, s[20:21]
	v_lshl_add_u64 v[12:13], v[12:13], 0, s[20:21]
	s_andn2_b64 exec, s[100:101], s[22:23]
	s_cbranch_execnz .LBB0_55
	s_or_b64 exec, exec, s[22:23]

.LBB0_438:
	s_waitcnt vmcnt(2)
	ds_write_b128 v176, v[2:5]
	ds_write_b128 v176, v[6:9] offset:33792
	ds_write_b128 v177, v[10:13]
	ds_write_b128 v177, v[14:17] offset:33792
	ds_write_b128 v178, v[18:21]
	ds_write_b128 v178, v[22:25] offset:33792
	ds_write_b128 v179, v[30:33]
	ds_write_b128 v179, v[34:37] offset:33792
	ds_write_b128 v180, v[26:29]
	v_lshlrev_b32_e32 v2, 16, v26
	v_and_b32_e32 v3, 0xffff0000, v26
	v_lshlrev_b32_e32 v4, 16, v27
	v_and_b32_e32 v5, 0xffff0000, v27
	v_pk_mul_f32 v[2:3], v[124:125], v[2:3]
	v_pk_mul_f32 v[4:5], v[124:125], v[4:5]
	v_cvt_pk_bf16_f32 v2, v2, v3
	v_cvt_pk_bf16_f32 v3, v4, v5
	v_lshlrev_b32_e32 v4, 16, v28
	v_and_b32_e32 v5, 0xffff0000, v28
	v_lshlrev_b32_e32 v6, 16, v29
	v_and_b32_e32 v7, 0xffff0000, v29
	v_pk_mul_f32 v[4:5], v[124:125], v[4:5]
	v_pk_mul_f32 v[6:7], v[124:125], v[6:7]
	v_cvt_pk_bf16_f32 v4, v4, v5
	v_cvt_pk_bf16_f32 v5, v6, v7
	v_lshl_add_u64 v[6:7], s[78:79], 0, v[122:123]
	ds_write_b128 v181, v[2:5]
	v_add_co_u32_e64 v2, s[36:37], s27, v6
	v_lshl_add_u64 v[14:15], s[78:79], 0, v[120:121]
	s_nop 0
	v_addc_co_u32_e64 v3, s[36:37], 0, v7, s[36:37]
	v_add_co_u32_e64 v6, s[36:37], s28, v6
	v_lshl_add_u64 v[22:23], s[78:79], 0, v[118:119]
	s_nop 0
	v_addc_co_u32_e64 v7, s[36:37], 0, v7, s[36:37]
	v_add_co_u32_e64 v10, s[36:37], s27, v14
	v_lshl_add_u64 v[26:27], s[78:79], 0, v[116:117]
	s_nop 0
	v_addc_co_u32_e64 v11, s[36:37], 0, v15, s[36:37]
	v_add_co_u32_e64 v14, s[36:37], s28, v14
	s_nop 0
	v_addc_co_u32_e64 v15, s[36:37], 0, v15, s[36:37]
	v_add_co_u32_e64 v18, s[36:37], s27, v22
	s_nop 0
	v_addc_co_u32_e64 v19, s[36:37], 0, v23, s[36:37]
	v_add_co_u32_e64 v22, s[36:37], s28, v22
	s_nop 1
	v_addc_co_u32_e64 v23, s[36:37], 0, v23, s[36:37]
	v_add_co_u32_e64 v28, s[36:37], s27, v26
	global_load_dwordx4 v[2:5], v[2:3], off
	s_nop 0
	v_addc_co_u32_e64 v29, s[36:37], 0, v27, s[36:37]
	v_add_co_u32_e64 v26, s[36:37], s28, v26
	global_load_dwordx4 v[30:33], v[28:29], off
	s_nop 0
	v_addc_co_u32_e64 v27, s[36:37], 0, v27, s[36:37]
	global_load_dwordx4 v[34:37], v[26:27], off
	v_lshl_add_u64 v[26:27], s[78:79], 0, v[114:115]
	global_load_dwordx4 v[6:9], v[6:7], off
	v_add_u32_e32 v205, v131, v127
	global_load_dwordx4 v[10:13], v[10:11], off
	s_mov_b32 s36, 0x59a00000
	global_load_dwordx4 v[14:17], v[14:15], off
	v_mov_b32_e32 v105, v104
	global_load_dwordx4 v[18:21], v[18:19], off
	v_pk_mul_f32 v[68:69], v[104:105], v[68:69]
	global_load_dwordx4 v[22:25], v[22:23], off
	v_pk_mul_f32 v[66:67], v[106:107], v[66:67]
	global_load_dwordx4 v[26:29], v[26:27], off
	s_waitcnt lgkmcnt(0)
	s_barrier
	ds_read_b128 v[70:73], v182
	ds_read_b128 v[74:77], v183 offset:33792
	ds_read_b128 v[188:191], v183 offset:42240
	ds_read_b128 v[210:213], v182 offset:16
	ds_read_b128 v[214:217], v183 offset:33808
	ds_read_b128 v[218:221], v183 offset:42256
	s_waitcnt lgkmcnt(4)
	v_mfma_f32_16x16x32_bf16 v[74:77], v[70:73], v[74:77], 0
	v_mul_f32_e64 v64, v104, v64
	v_mul_f32_e64 v65, v105, v65
	v_pk_mul_f32 v[62:63], v[106:107], v[62:63]
	v_pk_mul_f32 v[60:61], v[104:105], v[60:61]
	s_waitcnt lgkmcnt(3)
	v_mfma_f32_16x16x32_bf16 v[70:73], v[70:73], v[188:191], 0
	ds_read_b128 v[188:191], v182 offset:32
	ds_read_b128 v[192:195], v183 offset:33824
	ds_read_b128 v[206:209], v183 offset:42272
	v_pk_mul_f32 v[58:59], v[106:107], v[58:59]
	v_pk_mul_f32 v[48:49], v[104:105], v[48:49]
	s_waitcnt lgkmcnt(4)
	v_mfma_f32_16x16x32_bf16 v[74:77], v[210:213], v[214:217], v[74:77]
	v_mul_f32_e64 v46, v106, v46
	v_mul_f32_e64 v47, v107, v47
	v_pk_mul_f32 v[44:45], v[104:105], v[44:45]
	v_pk_mul_f32 v[42:43], v[106:107], v[42:43]
	s_waitcnt lgkmcnt(3)
	v_mfma_f32_16x16x32_bf16 v[70:73], v[210:213], v[218:221], v[70:73]
	ds_read_b128 v[210:213], v182 offset:48
	ds_read_b128 v[214:217], v183 offset:33840
	ds_read_b128 v[218:221], v183 offset:42288
	v_pk_mul_f32 v[40:41], v[104:105], v[40:41]
	v_pk_mul_f32 v[38:39], v[106:107], v[38:39]
	s_waitcnt lgkmcnt(4)
	v_mfma_f32_16x16x32_bf16 v[74:77], v[188:191], v[192:195], v[74:77]
	s_add_i32 s39, s39, -1
	v_lshl_add_u64 v[114:115], v[114:115], 0, s[34:35]
	v_lshl_add_u64 v[116:117], v[116:117], 0, s[86:87]
	s_waitcnt lgkmcnt(3)
	v_mfma_f32_16x16x32_bf16 v[70:73], v[188:191], v[206:209], v[70:73]
	ds_read_b128 v[188:191], v182 offset:64
	ds_read_b128 v[192:195], v183 offset:33856
	ds_read_b128 v[206:209], v183 offset:42304
	v_lshl_add_u64 v[118:119], v[118:119], 0, s[86:87]
	v_lshl_add_u64 v[120:121], v[120:121], 0, s[86:87]
	s_waitcnt lgkmcnt(4)
	v_mfma_f32_16x16x32_bf16 v[74:77], v[210:213], v[214:217], v[74:77]
	v_lshl_add_u64 v[122:123], v[122:123], 0, s[86:87]
	s_cmp_lg_u32 s39, 0
	s_waitcnt lgkmcnt(3)
	v_mfma_f32_16x16x32_bf16 v[70:73], v[210:213], v[218:221], v[70:73]
	ds_read_b128 v[210:213], v182 offset:80
	ds_read_b128 v[214:217], v183 offset:33872
	ds_read_b128 v[218:221], v183 offset:42320
	s_waitcnt lgkmcnt(4)
	v_mfma_f32_16x16x32_bf16 v[74:77], v[188:191], v[192:195], v[74:77]
	s_waitcnt lgkmcnt(3)
	v_mfma_f32_16x16x32_bf16 v[70:73], v[188:191], v[206:209], v[70:73]
	ds_read_b128 v[188:191], v182 offset:96
	ds_read_b128 v[192:195], v183 offset:33888
	ds_read_b128 v[206:209], v183 offset:42336
	s_waitcnt lgkmcnt(4)
	v_mfma_f32_16x16x32_bf16 v[74:77], v[210:213], v[214:217], v[74:77]
	s_waitcnt lgkmcnt(3)
	v_mfma_f32_16x16x32_bf16 v[70:73], v[210:213], v[218:221], v[70:73]
	ds_read_b128 v[210:213], v182 offset:112
	ds_read_b128 v[214:217], v183 offset:33904
	ds_read_b128 v[218:221], v183 offset:42352
	s_waitcnt lgkmcnt(4)
	v_mfma_f32_16x16x32_bf16 v[74:77], v[188:191], v[192:195], v[74:77]
	s_waitcnt lgkmcnt(3)
	v_mfma_f32_16x16x32_bf16 v[70:73], v[188:191], v[206:209], v[70:73]
	s_waitcnt lgkmcnt(1)
	v_mfma_f32_16x16x32_bf16 v[74:77], v[210:213], v[214:217], v[74:77]
	s_waitcnt lgkmcnt(0)
	v_mfma_f32_16x16x32_bf16 v[70:73], v[210:213], v[218:221], v[70:73]
	s_nop 5
	v_mul_f32_e32 v1, v103, v74
	v_cvt_pk_bf16_f32 v1, v1, s0
	v_add_u32_e32 v74, v131, v126
	ds_write_b16 v74, v1
	v_add_u32_e32 v206, v134, v127
	v_mul_f32_e32 v1, v198, v70
	v_cvt_pk_bf16_f32 v1, v1, s0
	ds_write_b16 v205, v1
	v_mul_f32_e32 v1, v199, v75
	v_cvt_pk_bf16_f32 v1, v1, s0
	v_add_u32_e32 v75, v134, v126
	ds_write_b16 v75, v1
	v_mul_f32_e32 v1, v200, v71
	v_cvt_pk_bf16_f32 v1, v1, s0
	ds_write_b16 v206, v1
	v_mul_f32_e32 v1, v201, v76
	v_cvt_pk_bf16_f32 v1, v1, s0
	v_add_u32_e32 v76, v137, v126
	ds_write_b16 v76, v1
	v_mul_f32_e32 v1, v202, v72
	v_cvt_pk_bf16_f32 v1, v1, s0
	v_add_u32_e32 v207, v137, v127
	ds_write_b16 v207, v1
	v_mul_f32_e32 v1, v203, v77
	v_cvt_pk_bf16_f32 v1, v1, s0
	v_add_u32_e32 v77, v140, v126
	ds_write_b16 v77, v1
	v_mul_f32_e32 v1, v204, v73
	v_cvt_pk_bf16_f32 v1, v1, s0
	v_add_u32_e32 v208, v140, v127
	ds_write_b16 v208, v1
	ds_read_b128 v[70:73], v182
	ds_read_b128 v[188:191], v184
	ds_read_b128 v[192:195], v184 offset:8448
	ds_read_b128 v[222:225], v182 offset:16
	ds_read_b128 v[218:221], v184 offset:16
	ds_read_b128 v[242:245], v184 offset:8464
	s_waitcnt lgkmcnt(4)
	v_mfma_f32_16x16x32_bf16 v[188:191], v[188:191], v[70:73], 0
	s_waitcnt lgkmcnt(3)
	v_mfma_f32_16x16x32_bf16 v[70:73], v[192:195], v[70:73], 0
	ds_read_b128 v[192:195], v182 offset:32
	ds_read_b128 v[210:213], v184 offset:32
	ds_read_b128 v[214:217], v184 offset:8480
	s_waitcnt lgkmcnt(4)
	v_mfma_f32_16x16x32_bf16 v[188:191], v[218:221], v[222:225], v[188:191]
	s_waitcnt lgkmcnt(3)
	v_mfma_f32_16x16x32_bf16 v[70:73], v[242:245], v[222:225], v[70:73]
	ds_read_b128 v[222:225], v182 offset:48
	ds_read_b128 v[218:221], v184 offset:48
	ds_read_b128 v[242:245], v184 offset:8496
	s_waitcnt lgkmcnt(4)
	v_mfma_f32_16x16x32_bf16 v[188:191], v[210:213], v[192:195], v[188:191]
	s_waitcnt lgkmcnt(3)
	v_mfma_f32_16x16x32_bf16 v[70:73], v[214:217], v[192:195], v[70:73]
	ds_read_b128 v[192:195], v182 offset:64
	ds_read_b128 v[210:213], v184 offset:64
	ds_read_b128 v[214:217], v184 offset:8512
	s_waitcnt lgkmcnt(4)
	v_mfma_f32_16x16x32_bf16 v[188:191], v[218:221], v[222:225], v[188:191]
	s_waitcnt lgkmcnt(3)
	v_mfma_f32_16x16x32_bf16 v[70:73], v[242:245], v[222:225], v[70:73]
	ds_read_b128 v[222:225], v182 offset:80
	ds_read_b128 v[218:221], v184 offset:80
	ds_read_b128 v[242:245], v184 offset:8528
	s_waitcnt lgkmcnt(4)
	v_mfma_f32_16x16x32_bf16 v[188:191], v[210:213], v[192:195], v[188:191]
	s_waitcnt lgkmcnt(3)
	v_mfma_f32_16x16x32_bf16 v[70:73], v[214:217], v[192:195], v[70:73]
	ds_read_b128 v[192:195], v182 offset:96
	ds_read_b128 v[210:213], v184 offset:96
	ds_read_b128 v[214:217], v184 offset:8544
	s_waitcnt lgkmcnt(4)
	v_mfma_f32_16x16x32_bf16 v[188:191], v[218:221], v[222:225], v[188:191]
	s_waitcnt lgkmcnt(3)
	v_mfma_f32_16x16x32_bf16 v[70:73], v[242:245], v[222:225], v[70:73]
	ds_read_b128 v[222:225], v182 offset:112
	ds_read_b128 v[218:221], v184 offset:112
	ds_read_b128 v[242:245], v184 offset:8560
	s_waitcnt lgkmcnt(4)
	v_mfma_f32_16x16x32_bf16 v[188:191], v[210:213], v[192:195], v[188:191]
	s_waitcnt lgkmcnt(3)
	v_mfma_f32_16x16x32_bf16 v[70:73], v[214:217], v[192:195], v[70:73]
	ds_read_b64_tr_b16 v[214:215], v141
	ds_read_b64_tr_b16 v[216:217], v142
	ds_read_b64_tr_b16 v[210:211], v143
	ds_read_b64_tr_b16 v[212:213], v144
	s_waitcnt lgkmcnt(5)
	v_mfma_f32_16x16x32_bf16 v[188:191], v[218:221], v[222:225], v[188:191]
	s_waitcnt lgkmcnt(4)
	v_mfma_f32_16x16x32_bf16 v[70:73], v[242:245], v[222:225], v[70:73]
	ds_read_b64_tr_b16 v[218:219], v145
	ds_read_b64_tr_b16 v[220:221], v146
	ds_read_b64_tr_b16 v[242:243], v147
	ds_read_b64_tr_b16 v[244:245], v148
	s_barrier
	ds_read_b128 v[192:195], v185
	ds_read_b128 v[222:225], v185 offset:64
	s_nop 7
	v_pk_mul_f32 v[190:191], v[110:111], v[190:191]
	v_pk_mul_f32 v[188:189], v[108:109], v[188:189]
	v_mul_f32_e64 v72, v110, v72
	v_mul_f32_e64 v73, v111, v73
	v_pk_mul_f32 v[70:71], v[108:109], v[70:71]
	s_waitcnt lgkmcnt(1)
	s_nop 1
	v_mfma_f32_16x16x32_bf16 v[188:191], v[214:217], v[192:195], v[188:191]
	v_mfma_f32_16x16x32_bf16 v[70:73], v[210:213], v[192:195], v[70:73]
	s_waitcnt lgkmcnt(0)
	v_mfma_f32_16x16x32_bf16 v[188:191], v[218:221], v[222:225], v[188:191]
	v_mfma_f32_16x16x32_bf16 v[192:195], v[242:245], v[222:225], v[70:73]
	s_nop 6
	v_cvt_pk_bf16_f32 v70, v188, v189
	v_lshl_add_u64 v[188:189], s[78:79], 0, v[112:113]
	v_add_co_u32_e64 v188, s[36:37], s36, v188
	v_cvt_pk_bf16_f32 v71, v190, v191
	s_nop 0
	v_addc_co_u32_e64 v189, s[36:37], 0, v189, s[36:37]
	v_cvt_pk_bf16_f32 v72, v192, v193
	v_cvt_pk_bf16_f32 v73, v194, v195
	global_store_dwordx2 v[188:189], v[70:71], off
	global_store_dwordx2 v[188:189], v[72:73], off offset:32
	v_pk_mul_f32 v[72:73], v[104:105], v[52:53]
	v_pk_mul_f32 v[70:71], v[106:107], v[50:51]
	v_pk_mul_f32 v[52:53], v[104:105], v[56:57]
	v_pk_mul_f32 v[50:51], v[106:107], v[54:55]
	ds_read_b64_tr_b16 v[188:189], v149
	ds_read_b64_tr_b16 v[190:191], v151
	ds_read_b64_tr_b16 v[54:55], v152
	ds_read_b64_tr_b16 v[56:57], v153
	ds_read_b64_tr_b16 v[210:211], v150
	ds_read_b64_tr_b16 v[212:213], v154
	ds_read_b64_tr_b16 v[192:193], v155
	ds_read_b64_tr_b16 v[194:195], v156
	ds_read_b64_tr_b16 v[218:219], v157
	ds_read_b64_tr_b16 v[220:221], v158
	ds_read_b64_tr_b16 v[214:215], v159
	ds_read_b64_tr_b16 v[216:217], v160
	s_waitcnt lgkmcnt(0)
	v_lshl_add_u64 v[112:113], v[112:113], 0, s[34:35]
	v_mfma_f32_16x16x32_bf16 v[66:69], v[188:191], v[210:213], v[66:69]
	v_mfma_f32_16x16x32_bf16 v[62:65], v[188:191], v[192:195], v[62:65]
	v_mfma_f32_16x16x32_bf16 v[58:61], v[188:191], v[218:221], v[58:61]
	v_mfma_f32_16x16x32_bf16 v[70:73], v[188:191], v[214:217], v[70:73]
	v_mfma_f32_16x16x32_bf16 v[188:191], v[54:57], v[210:213], v[50:53]
	v_mfma_f32_16x16x32_bf16 v[46:49], v[54:57], v[192:195], v[46:49]
	ds_read_b64_tr_b16 v[50:51], v161
	ds_read_b64_tr_b16 v[52:53], v163
	ds_read_b64_tr_b16 v[192:193], v164
	ds_read_b64_tr_b16 v[194:195], v165
	s_waitcnt lgkmcnt(0)
	v_mfma_f32_16x16x32_bf16 v[42:45], v[54:57], v[218:221], v[42:45]
	v_mfma_f32_16x16x32_bf16 v[38:41], v[54:57], v[214:217], v[38:41]
	ds_read_b64_tr_b16 v[54:55], v162
	ds_read_b64_tr_b16 v[56:57], v166
	ds_read_b64_tr_b16 v[210:211], v167
	ds_read_b64_tr_b16 v[212:213], v168
	s_waitcnt lgkmcnt(0)
	ds_read_b64_tr_b16 v[218:219], v169
	ds_read_b64_tr_b16 v[220:221], v170
	ds_read_b64_tr_b16 v[214:215], v171
	ds_read_b64_tr_b16 v[216:217], v172
	s_waitcnt lgkmcnt(0)
	s_nop 0
	v_mfma_f32_16x16x32_bf16 v[66:69], v[50:53], v[54:57], v[66:69]
	s_barrier
	v_mfma_f32_16x16x32_bf16 v[62:65], v[50:53], v[210:213], v[62:65]
	v_mfma_f32_16x16x32_bf16 v[58:61], v[50:53], v[218:221], v[58:61]
	v_mfma_f32_16x16x32_bf16 v[50:53], v[50:53], v[214:217], v[70:73]
	v_mfma_f32_16x16x32_bf16 v[54:57], v[192:195], v[54:57], v[188:191]
	s_nop 2
	v_cvt_pk_bf16_f32 v70, v66, v67
	v_cvt_pk_bf16_f32 v71, v68, v69
	ds_write_b64 v196, v[70:71]
	v_mfma_f32_16x16x32_bf16 v[46:49], v[192:195], v[210:213], v[46:49]
	v_cvt_pk_bf16_f32 v70, v62, v63
	v_cvt_pk_bf16_f32 v71, v64, v65
	ds_write_b64 v196, v[70:71] offset:8448
	v_mfma_f32_16x16x32_bf16 v[42:45], v[192:195], v[218:221], v[42:45]
	v_cvt_pk_bf16_f32 v70, v58, v59
	v_cvt_pk_bf16_f32 v71, v60, v61
	ds_write_b64 v196, v[70:71] offset:16896
	v_mfma_f32_16x16x32_bf16 v[38:41], v[192:195], v[214:217], v[38:41]
	v_cvt_pk_bf16_f32 v70, v50, v51
	v_cvt_pk_bf16_f32 v71, v52, v53
	ds_write_b64 v196, v[70:71] offset:25344
	v_cvt_pk_bf16_f32 v70, v54, v55
	v_cvt_pk_bf16_f32 v71, v56, v57
	ds_write_b64 v197, v[70:71]
	v_cvt_pk_bf16_f32 v70, v46, v47
	v_cvt_pk_bf16_f32 v71, v48, v49
	ds_write_b64 v197, v[70:71] offset:8448
	v_cvt_pk_bf16_f32 v70, v42, v43
	v_cvt_pk_bf16_f32 v71, v44, v45
	ds_write_b64 v197, v[70:71] offset:16896
	v_cvt_pk_bf16_f32 v70, v38, v39
	v_cvt_pk_bf16_f32 v71, v40, v41
	ds_write_b64 v197, v[70:71] offset:25344
	s_cbranch_scc1 .LBB0_438
	s_waitcnt vmcnt(10)
	ds_write_b128 v176, v[2:5]
	s_waitcnt vmcnt(7)
	ds_write_b128 v176, v[6:9] offset:33792
	s_waitcnt vmcnt(6)
	ds_write_b128 v177, v[10:13]
	s_waitcnt vmcnt(5)
	ds_write_b128 v177, v[14:17] offset:33792
	s_waitcnt vmcnt(4)
	ds_write_b128 v178, v[18:21]
	s_waitcnt vmcnt(3)
	ds_write_b128 v178, v[22:25] offset:33792
	ds_write_b128 v179, v[30:33]
	ds_write_b128 v179, v[34:37] offset:33792
	s_waitcnt vmcnt(2)
	ds_write_b128 v180, v[26:29]
	v_lshlrev_b32_e32 v2, 16, v26
	v_and_b32_e32 v3, 0xffff0000, v26
	v_lshlrev_b32_e32 v4, 16, v27
	v_and_b32_e32 v5, 0xffff0000, v27
	v_pk_mul_f32 v[2:3], v[124:125], v[2:3]
	v_pk_mul_f32 v[4:5], v[124:125], v[4:5]
	v_cvt_pk_bf16_f32 v2, v2, v3
	v_cvt_pk_bf16_f32 v3, v4, v5
	v_lshlrev_b32_e32 v4, 16, v28
	v_and_b32_e32 v5, 0xffff0000, v28
	v_lshlrev_b32_e32 v6, 16, v29
	v_and_b32_e32 v7, 0xffff0000, v29
	v_pk_mul_f32 v[4:5], v[124:125], v[4:5]
	v_pk_mul_f32 v[6:7], v[124:125], v[6:7]
	v_cvt_pk_bf16_f32 v4, v4, v5
	v_cvt_pk_bf16_f32 v5, v6, v7
	ds_write_b128 v181, v[2:5]
	s_waitcnt lgkmcnt(0)
	s_barrier
	ds_read_b128 v[2:5], v182
	ds_read_b128 v[6:9], v183 offset:33792
	ds_read_b128 v[10:13], v182 offset:16
	ds_read_b128 v[14:17], v183 offset:33808
	s_waitcnt lgkmcnt(2)
	v_mfma_f32_16x16x32_bf16 v[6:9], v[2:5], v[6:9], 0
	ds_read_b128 v[18:21], v183 offset:42240
	ds_read_b128 v[22:25], v183 offset:42256
	s_lshl_b32 s15, s15, 1
	s_add_u32 s15, s7, s15
	s_waitcnt lgkmcnt(2)
	v_mfma_f32_16x16x32_bf16 v[6:9], v[10:13], v[14:17], v[6:9]
	ds_read_b128 v[14:17], v182 offset:32
	s_addc_u32 s39, s10, 0
	s_lshl_b64 s[36:37], s[40:41], 1
	s_waitcnt lgkmcnt(2)
	v_mfma_f32_16x16x32_bf16 v[2:5], v[2:5], v[18:21], 0
	s_add_u32 s36, s15, s36
	s_addc_u32 s37, s39, s37
	v_pk_mul_f32 v[30:31], v[104:105], v[60:61]
	s_waitcnt lgkmcnt(1)
	v_mfma_f32_16x16x32_bf16 v[2:5], v[10:13], v[22:25], v[2:5]
	ds_read_b128 v[10:13], v183 offset:33824
	ds_read_b128 v[18:21], v182 offset:48
	ds_read_b128 v[22:25], v183 offset:33840
	v_pk_mul_f32 v[52:53], v[104:105], v[52:53]
	v_pk_mul_f32 v[50:51], v[106:107], v[50:51]
	s_waitcnt lgkmcnt(2)
	v_mfma_f32_16x16x32_bf16 v[6:9], v[14:17], v[10:13], v[6:9]
	ds_read_b128 v[10:13], v183 offset:42272
	ds_read_b128 v[26:29], v183 offset:42288
	v_pk_mul_f32 v[48:49], v[104:105], v[48:49]
	v_pk_mul_f32 v[46:47], v[106:107], v[46:47]
	s_waitcnt lgkmcnt(1)
	v_mfma_f32_16x16x32_bf16 v[2:5], v[14:17], v[10:13], v[2:5]
	ds_read_b128 v[10:13], v182 offset:64
	v_pk_mul_f32 v[44:45], v[104:105], v[44:45]
	v_pk_mul_f32 v[42:43], v[106:107], v[42:43]
	v_mfma_f32_16x16x32_bf16 v[6:9], v[18:21], v[22:25], v[6:9]
	v_mul_f32_e64 v40, v104, v40
	v_mul_f32_e64 v41, v105, v41
	v_pk_mul_f32 v[38:39], v[106:107], v[38:39]
	s_add_i32 s14, s14, s85
	s_waitcnt lgkmcnt(1)
	v_mfma_f32_16x16x32_bf16 v[2:5], v[18:21], v[26:29], v[2:5]
	ds_read_b128 v[14:17], v183 offset:33856
	ds_read_b128 v[18:21], v182 offset:80
	ds_read_b128 v[22:25], v183 offset:33872
	s_add_i32 s13, s13, s50
	s_add_i32 s12, s12, s85
	s_waitcnt lgkmcnt(2)
	v_mfma_f32_16x16x32_bf16 v[6:9], v[10:13], v[14:17], v[6:9]
	ds_read_b128 v[14:17], v183 offset:42304
	ds_read_b128 v[26:29], v183 offset:42320
	s_add_i32 s11, s11, s51
	s_waitcnt lgkmcnt(1)
	v_mfma_f32_16x16x32_bf16 v[2:5], v[10:13], v[14:17], v[2:5]
	ds_read_b128 v[10:13], v182 offset:96
	v_mfma_f32_16x16x32_bf16 v[6:9], v[18:21], v[22:25], v[6:9]
	s_waitcnt lgkmcnt(1)
	v_mfma_f32_16x16x32_bf16 v[2:5], v[18:21], v[26:29], v[2:5]
	ds_read_b128 v[14:17], v183 offset:33888
	ds_read_b128 v[18:21], v182 offset:112
	ds_read_b128 v[22:25], v183 offset:33904
	s_waitcnt lgkmcnt(2)
	v_mfma_f32_16x16x32_bf16 v[6:9], v[10:13], v[14:17], v[6:9]
	ds_read_b128 v[14:17], v183 offset:42336
	ds_read_b128 v[26:29], v183 offset:42352
	s_waitcnt lgkmcnt(1)
	v_mfma_f32_16x16x32_bf16 v[2:5], v[10:13], v[14:17], v[2:5]
	v_mfma_f32_16x16x32_bf16 v[6:9], v[18:21], v[22:25], v[6:9]
	s_waitcnt lgkmcnt(0)
	v_mfma_f32_16x16x32_bf16 v[2:5], v[18:21], v[26:29], v[2:5]
	s_nop 5
	v_mul_f32_e32 v1, v103, v6
	v_cvt_pk_bf16_f32 v1, v1, s0
	ds_write_b16 v74, v1
	v_mul_f32_e32 v1, v198, v2
	v_cvt_pk_bf16_f32 v1, v1, s0
	ds_write_b16 v205, v1
	v_mul_f32_e32 v1, v199, v7
	v_cvt_pk_bf16_f32 v1, v1, s0
	ds_write_b16 v75, v1
	v_mul_f32_e32 v1, v200, v3
	v_cvt_pk_bf16_f32 v1, v1, s0
	ds_write_b16 v206, v1
	v_mul_f32_e32 v1, v201, v8
	v_cvt_pk_bf16_f32 v1, v1, s0
	ds_write_b16 v76, v1
	v_mul_f32_e32 v1, v202, v4
	v_cvt_pk_bf16_f32 v1, v1, s0
	ds_write_b16 v207, v1
	v_mul_f32_e32 v1, v203, v9
	v_cvt_pk_bf16_f32 v1, v1, s0
	ds_write_b16 v77, v1
	v_mul_f32_e32 v1, v204, v5
	v_cvt_pk_bf16_f32 v1, v1, s0
	ds_write_b16 v208, v1
	s_waitcnt lgkmcnt(0)
	s_barrier
	ds_read_b128 v[2:5], v184
	ds_read_b128 v[6:9], v182
	ds_read_b128 v[10:13], v182 offset:16
	ds_read_b128 v[14:17], v184 offset:16
	s_waitcnt lgkmcnt(2)
	v_mfma_f32_16x16x32_bf16 v[2:5], v[2:5], v[6:9], 0
	ds_read_b128 v[18:21], v184 offset:8448
	ds_read_b128 v[22:25], v184 offset:8464
	s_waitcnt lgkmcnt(2)
	v_mfma_f32_16x16x32_bf16 v[2:5], v[14:17], v[10:13], v[2:5]
	ds_read_b128 v[14:17], v184 offset:32
	s_waitcnt lgkmcnt(2)
	v_mfma_f32_16x16x32_bf16 v[6:9], v[18:21], v[6:9], 0
	s_waitcnt lgkmcnt(1)
	v_mfma_f32_16x16x32_bf16 v[6:9], v[22:25], v[10:13], v[6:9]
	ds_read_b128 v[10:13], v182 offset:32
	ds_read_b128 v[18:21], v182 offset:48
	ds_read_b128 v[22:25], v184 offset:48
	s_waitcnt lgkmcnt(2)
	v_mfma_f32_16x16x32_bf16 v[2:5], v[14:17], v[10:13], v[2:5]
	ds_read_b128 v[14:17], v184 offset:8480
	ds_read_b128 v[26:29], v184 offset:8496
	s_waitcnt lgkmcnt(1)
	v_mfma_f32_16x16x32_bf16 v[6:9], v[14:17], v[10:13], v[6:9]
	ds_read_b128 v[10:13], v184 offset:64
	v_mfma_f32_16x16x32_bf16 v[2:5], v[22:25], v[18:21], v[2:5]
	s_waitcnt lgkmcnt(1)
	v_mfma_f32_16x16x32_bf16 v[6:9], v[26:29], v[18:21], v[6:9]
	ds_read_b128 v[14:17], v182 offset:64
	ds_read_b128 v[18:21], v182 offset:80
	ds_read_b128 v[22:25], v184 offset:80
	s_waitcnt lgkmcnt(2)
	v_mfma_f32_16x16x32_bf16 v[2:5], v[10:13], v[14:17], v[2:5]
	ds_read_b128 v[10:13], v184 offset:8512
	ds_read_b128 v[26:29], v184 offset:8528
	s_waitcnt lgkmcnt(1)
	v_mfma_f32_16x16x32_bf16 v[6:9], v[10:13], v[14:17], v[6:9]
	ds_read_b128 v[10:13], v184 offset:96
	v_mfma_f32_16x16x32_bf16 v[2:5], v[22:25], v[18:21], v[2:5]
	s_waitcnt lgkmcnt(1)
	v_mfma_f32_16x16x32_bf16 v[6:9], v[26:29], v[18:21], v[6:9]
	ds_read_b128 v[14:17], v182 offset:96
	ds_read_b128 v[18:21], v182 offset:112
	ds_read_b128 v[22:25], v184 offset:112
	s_waitcnt lgkmcnt(2)
	v_mfma_f32_16x16x32_bf16 v[2:5], v[10:13], v[14:17], v[2:5]
	ds_read_b128 v[10:13], v184 offset:8544
	ds_read_b128 v[26:29], v184 offset:8560
	s_waitcnt lgkmcnt(1)
	v_mfma_f32_16x16x32_bf16 v[6:9], v[10:13], v[14:17], v[6:9]
	ds_read_b128 v[10:13], v185
	v_mfma_f32_16x16x32_bf16 v[2:5], v[22:25], v[18:21], v[2:5]
	s_waitcnt lgkmcnt(1)
	v_mfma_f32_16x16x32_bf16 v[6:9], v[26:29], v[18:21], v[6:9]
	ds_read_b64_tr_b16 v[18:19], v141
	ds_read_b64_tr_b16 v[20:21], v142
	ds_read_b64_tr_b16 v[14:15], v143
	ds_read_b64_tr_b16 v[16:17], v144
	s_waitcnt lgkmcnt(0)
	s_nop 5
	v_mul_f32_e64 v4, v110, v4
	v_mul_f32_e64 v5, v111, v5
	v_pk_mul_f32 v[2:3], v[108:109], v[2:3]
	v_pk_mul_f32 v[28:29], v[106:107], v[58:59]
	s_waitcnt lgkmcnt(0)
	v_mfma_f32_16x16x32_bf16 v[2:5], v[18:21], v[10:13], v[2:5]
	v_mul_f32_e64 v8, v110, v8
	v_mul_f32_e64 v9, v111, v9
	v_pk_mul_f32 v[6:7], v[108:109], v[6:7]
	s_nop 1
	v_mfma_f32_16x16x32_bf16 v[6:9], v[14:17], v[10:13], v[6:9]
	ds_read_b128 v[10:13], v185 offset:64
	ds_read_b64_tr_b16 v[18:19], v145
	ds_read_b64_tr_b16 v[20:21], v146
	ds_read_b64_tr_b16 v[14:15], v147
	ds_read_b64_tr_b16 v[16:17], v148
	s_waitcnt lgkmcnt(0)
	s_waitcnt lgkmcnt(0)
	v_mfma_f32_16x16x32_bf16 v[2:5], v[18:21], v[10:13], v[2:5]
	v_lshl_add_u64 v[18:19], s[36:37], 0, v[186:187]
	s_or_b32 s36, s38, 0xfc0
	s_mov_b32 s37, s57
	v_mfma_f32_16x16x32_bf16 v[6:9], v[14:17], v[10:13], v[6:9]
	v_lshl_add_u64 v[10:11], v[80:81], 0, s[36:37]
	v_lshl_add_u64 v[18:19], v[18:19], 0, s[56:57]
	s_nop 1
	v_cvt_pk_bf16_f32 v2, v2, v3
	v_cvt_pk_bf16_f32 v3, v4, v5
	s_cmpk_lt_i32 s14, 0x100
	s_nop 0
	v_cvt_pk_bf16_f32 v4, v6, v7
	v_lshlrev_b64 v[6:7], 13, v[10:11]
	v_lshl_add_u64 v[6:7], v[18:19], 0, v[6:7]
	v_cvt_pk_bf16_f32 v5, v8, v9
	global_store_dwordx2 v[6:7], v[2:3], off
	global_store_dwordx2 v[6:7], v[4:5], off offset:32
	v_pk_mul_f32 v[4:5], v[104:105], v[68:69]
	v_pk_mul_f32 v[2:3], v[106:107], v[66:67]
	ds_read_b64_tr_b16 v[12:13], v149
	ds_read_b64_tr_b16 v[14:15], v151
	ds_read_b64_tr_b16 v[8:9], v152
	ds_read_b64_tr_b16 v[10:11], v153
	s_waitcnt lgkmcnt(0)
	v_pk_mul_f32 v[6:7], v[104:105], v[64:65]
	ds_read_b64_tr_b16 v[20:21], v150
	ds_read_b64_tr_b16 v[22:23], v154
	ds_read_b64_tr_b16 v[16:17], v155
	ds_read_b64_tr_b16 v[18:19], v156
	s_waitcnt lgkmcnt(0)
	ds_read_b64_tr_b16 v[58:59], v157
	ds_read_b64_tr_b16 v[60:61], v158
	ds_read_b64_tr_b16 v[32:33], v159
	ds_read_b64_tr_b16 v[34:35], v160
	s_waitcnt lgkmcnt(0)
	s_nop 0
	v_mfma_f32_16x16x32_bf16 v[24:27], v[12:15], v[20:23], v[2:5]
	s_nop 2
	v_mul_f32_e64 v4, v106, v62
	v_mul_f32_e64 v5, v107, v63
	v_mfma_f32_16x16x32_bf16 v[28:31], v[12:15], v[58:61], v[28:31]
	s_nop 0
	v_mfma_f32_16x16x32_bf16 v[2:5], v[12:15], v[16:19], v[4:7]
	v_mfma_f32_16x16x32_bf16 v[12:15], v[12:15], v[32:35], v[50:53]
	s_nop 2
	v_mul_f32_e64 v52, v104, v56
	v_mul_f32_e64 v53, v105, v57
	v_pk_mul_f32 v[50:51], v[106:107], v[54:55]
	v_mfma_f32_16x16x32_bf16 v[16:19], v[8:11], v[16:19], v[46:49]
	s_nop 0
	v_mfma_f32_16x16x32_bf16 v[20:23], v[8:11], v[20:23], v[50:53]
	v_mfma_f32_16x16x32_bf16 v[42:45], v[8:11], v[58:61], v[42:45]
	v_mfma_f32_16x16x32_bf16 v[6:9], v[8:11], v[32:35], v[38:41]
	ds_read_b64_tr_b16 v[36:37], v161
	ds_read_b64_tr_b16 v[38:39], v163
	ds_read_b64_tr_b16 v[32:33], v164
	ds_read_b64_tr_b16 v[34:35], v165
	s_waitcnt lgkmcnt(0)
	ds_read_b64_tr_b16 v[50:51], v162
	ds_read_b64_tr_b16 v[52:53], v166
	ds_read_b64_tr_b16 v[46:47], v167
	ds_read_b64_tr_b16 v[48:49], v168
	s_waitcnt lgkmcnt(0)
	ds_read_b64_tr_b16 v[58:59], v169
	ds_read_b64_tr_b16 v[60:61], v170
	ds_read_b64_tr_b16 v[54:55], v171
	ds_read_b64_tr_b16 v[56:57], v172
	s_waitcnt lgkmcnt(0)
	s_nop 0
	v_mfma_f32_16x16x32_bf16 v[2:5], v[36:39], v[46:49], v[2:5]
	s_barrier
	v_mfma_f32_16x16x32_bf16 v[28:31], v[36:39], v[58:61], v[28:31]
	v_mfma_f32_16x16x32_bf16 v[10:13], v[36:39], v[54:57], v[12:15]
	s_nop 4
	v_cvt_pk_bf16_f32 v2, v2, v3
	v_cvt_pk_bf16_f32 v3, v4, v5
	ds_write_b64 v196, v[2:3] offset:8448
	v_mfma_f32_16x16x32_bf16 v[20:23], v[32:35], v[50:53], v[20:23]
	v_cvt_pk_bf16_f32 v2, v28, v29
	v_cvt_pk_bf16_f32 v3, v30, v31
	ds_write_b64 v196, v[2:3] offset:16896
	v_mfma_f32_16x16x32_bf16 v[14:17], v[32:35], v[46:49], v[16:19]
	v_cvt_pk_bf16_f32 v2, v10, v11
	v_cvt_pk_bf16_f32 v3, v12, v13
	ds_write_b64 v196, v[2:3] offset:25344
	v_mfma_f32_16x16x32_bf16 v[24:27], v[36:39], v[50:53], v[24:27]
	v_cvt_pk_bf16_f32 v2, v20, v21
	v_cvt_pk_bf16_f32 v3, v22, v23
	ds_write_b64 v197, v[2:3]
	v_mfma_f32_16x16x32_bf16 v[36:39], v[32:35], v[58:61], v[42:45]
	v_cvt_pk_bf16_f32 v2, v14, v15
	v_cvt_pk_bf16_f32 v3, v16, v17
	ds_write_b64 v197, v[2:3] offset:8448
	v_mfma_f32_16x16x32_bf16 v[6:9], v[32:35], v[54:57], v[6:9]
	v_cvt_pk_bf16_f32 v18, v24, v25
	s_nop 2
	v_cvt_pk_bf16_f32 v2, v36, v37
	v_cvt_pk_bf16_f32 v3, v38, v39
	v_cvt_pk_bf16_f32 v19, v26, v27
	ds_write_b64 v197, v[2:3] offset:16896
	v_cvt_pk_bf16_f32 v2, v6, v7
	v_cvt_pk_bf16_f32 v3, v8, v9
	ds_write_b64 v196, v[18:19]
	ds_write_b64 v197, v[2:3] offset:25344
	s_waitcnt lgkmcnt(0)
	s_barrier
	s_cbranch_scc1 .LBB0_434
